# P0 convert: third-round weight tiles moved to workgroups with fewer row batches (gw^1024)
# speedup vs baseline: 1.0165x; 1.0030x over previous
; #define LAS __attribute__((address_space(3)))
; __device__ __forceinline__ void p0_convert(const Args& a, LAS float* scr, int gw, int NGW, int lane) {
;     constexpr int I_IN = 104 * 16, I_PA = 16 * 8, I_PB = 16 * 16, I_OUT = 16 * 16, I_GU = 88 * 16, I_DN = 16 * 44, TOTAL = I_IN + I_PA + I_PB + I_OUT + I_GU + I_DN;
;     for (int it = gw; it < TOTAL; it += NGW) {
;         int r = it, kind, K; size_t dsto;
;         if (r < I_IN) { kind = 0; K = 1024; dsto = WS_WIN; }
;         else if ((r -= I_IN) < I_PA) { kind = 1; K = 512; dsto = WS_WPA; }
;         else if ((r -= I_PA) < I_PB) { kind = 2; K = 1024; dsto = WS_WPB; }
;         else if ((r -= I_PB) < I_OUT) { kind = 3; K = 1024; dsto = WS_WOUT; }
;         else if ((r -= I_OUT) < I_GU) { kind = 4; K = 1024; dsto = WS_WGU; }
;         else { r -= I_GU; kind = 5; K = 2816; dsto = WS_WDN; }
;         const int ktiles = K >> 6, n0 = (r / ktiles) * 64, k0 = (r % ktiles) * 64, n = n0 + lane;
.LBB0_88:
	s_or_b64 exec, exec, s[6:7]
	s_cmpk_gt_i32 s81, 0x113f
	s_cbranch_scc1 .LBB0_129
	v_and_b32_e32 v0, 31, v178
	s_mul_i32 s0, s93, 0x4100
	v_lshlrev_b32_e32 v5, 3, v0
	v_lshlrev_b32_e32 v0, 2, v0
	v_mov_b32_e32 v1, 0
	s_movk_i32 s6, 0x104
	v_lshrrev_b32_e32 v20, 5, v176
	v_lshl_add_u64 v[2:3], s[54:55], 0, v[0:1]
	v_mov_b32_e32 v0, s0
	s_add_i32 s3, s0, 0
	v_mul_u32_u24_e32 v4, 0x104, v176
	v_mad_u32_u24 v0, v20, s6, v0
	s_mov_b32 s1, 0
	v_or_b32_e32 v21, 14, v20
	v_add3_u32 v22, v0, v5, 0
	v_or_b32_e32 v23, 12, v20
	v_or_b32_e32 v24, 10, v20
	v_or_b32_e32 v25, 8, v20
	v_or_b32_e32 v26, 6, v20
	v_or_b32_e32 v27, 4, v20
	v_or_b32_e32 v28, 2, v20
	s_movk_i32 s72, 0x1200
	v_add_u32_e32 v29, s3, v4
	s_xor_b32 s73, s81, 0x400
